# grid barrier: issue each WG's L1 invalidate (buffer_inv sc1) right after its arrival instead of after the release, so it overlaps the wait
# speedup vs baseline: 1.0140x; 1.0140x over previous
.Lgs0_b173:
	s_or_b64 exec, exec, s[18:19]
	v_cvt_f32_u32_e32 v4, v2
	s_waitcnt vmcnt(0)
	v_readfirstlane_b32 s18, v3
	v_sub_u32_e32 v3, 0, v2
	v_rcp_iflag_f32_e32 v4, v4
	v_add_u32_e32 v5, s18, v1
	v_mul_f32_e32 v4, 0x4f7ffffe, v4
	v_cvt_u32_f32_e32 v4, v4
	v_mul_lo_u32 v1, v3, v4
	v_mul_hi_u32 v1, v4, v1
	v_add_u32_e32 v1, v4, v1
	v_mul_hi_u32 v1, v5, v1
	v_mul_lo_u32 v3, v1, v2
	v_sub_u32_e32 v3, v5, v3
	v_add_u32_e32 v4, 1, v1
	v_cmp_ge_u32_e32 vcc, v3, v2
	s_nop 1
	v_cndmask_b32_e32 v1, v1, v4, vcc
	v_sub_u32_e32 v4, v3, v2
	v_cndmask_b32_e32 v3, v3, v4, vcc
	v_add_u32_e32 v4, 1, v1
	v_cmp_ge_u32_e32 vcc, v3, v2
	v_add_u32_e32 v3, 1, v5
	s_nop 0
	v_cndmask_b32_e32 v1, v1, v4, vcc
	v_mul_lo_u32 v4, v2, v1
	v_add_u32_e32 v2, v4, v2
	v_cmp_ne_u32_e32 vcc, v3, v2
	s_and_saveexec_b64 s[18:19], vcc
	s_xor_b64 s[18:19], exec, s[18:19]
	s_cbranch_execz .Lgs0_b187
	buffer_inv sc1
	v_readlane_b32 s22, v255, 0
	v_readlane_b32 s23, v255, 1
	s_waitcnt lgkmcnt(0)
	s_nop 3
	global_load_dword v0, v17, s[22:23] sc1
	s_waitcnt vmcnt(0)
	v_cmp_eq_u32_e32 vcc, v0, v1
	s_and_saveexec_b64 s[22:23], vcc
	s_cbranch_execz .Lgs0_b186
	s_mov_b32 s24, 1
	s_mov_b64 s[28:29], 0
	s_branch .Lgs0_b177

.Lgs0_b186:
	s_or_b64 exec, exec, s[22:23]
	s_waitcnt vmcnt(0)
	s_waitcnt vmcnt(0)
.Lgs0_b187:
	s_andn2_saveexec_b64 s[18:19], s[18:19]
	s_cbranch_execz .Lgs0_end
	s_mov_b64 s[18:19], exec
	buffer_wbl2 sc1
	buffer_inv sc1
	s_waitcnt lgkmcnt(0)
	s_waitcnt vmcnt(0)
	v_mbcnt_lo_u32_b32 v1, s18, 0
	v_mbcnt_hi_u32_b32 v1, s19, v1
	v_cmp_eq_u32_e32 vcc, 0, v1
	s_and_saveexec_b64 s[22:23], vcc
	s_cbranch_execz .Lgs0_b190
	s_bcnt1_i32_b64 s18, s[18:19]
	v_mov_b32_e32 v2, s18
	v_readlane_b32 s18, v255, 2
	v_readlane_b32 s19, v255, 3
	s_nop 4
	global_atomic_add v2, v17, v2, s[18:19] sc0

.Lgs0_b204:
	s_or_b64 exec, exec, s[18:19]
	s_mov_b64 s[18:19], exec
	v_mbcnt_lo_u32_b32 v0, s18, 0
	v_mbcnt_hi_u32_b32 v0, s19, v0
	v_cmp_eq_u32_e32 vcc, 0, v0
	s_waitcnt vmcnt(0)
	s_and_saveexec_b64 s[22:23], vcc
	s_cbranch_execz .Lgs0_b206
	s_bcnt1_i32_b64 s18, s[18:19]
	v_mov_b32_e32 v0, s18
	v_readlane_b32 s18, v255, 0
	v_readlane_b32 s19, v255, 1
	s_nop 4
	global_atomic_add v17, v0, s[18:19]

.LBB0_604:
	s_or_b64 exec, exec, s[18:19]
	v_cvt_f32_u32_e32 v4, v2
	s_waitcnt vmcnt(0)
	v_readfirstlane_b32 s18, v3
	v_sub_u32_e32 v3, 0, v2
	v_rcp_iflag_f32_e32 v4, v4
	v_add_u32_e32 v5, s18, v1
	v_mul_f32_e32 v4, 0x4f7ffffe, v4
	v_cvt_u32_f32_e32 v4, v4
	v_mul_lo_u32 v1, v3, v4
	v_mul_hi_u32 v1, v4, v1
	v_add_u32_e32 v1, v4, v1
	v_mul_hi_u32 v1, v5, v1
	v_mul_lo_u32 v3, v1, v2
	v_sub_u32_e32 v3, v5, v3
	v_add_u32_e32 v4, 1, v1
	v_cmp_ge_u32_e32 vcc, v3, v2
	s_nop 1
	v_cndmask_b32_e32 v1, v1, v4, vcc
	v_sub_u32_e32 v4, v3, v2
	v_cndmask_b32_e32 v3, v3, v4, vcc
	v_add_u32_e32 v4, 1, v1
	v_cmp_ge_u32_e32 vcc, v3, v2
	v_add_u32_e32 v3, 1, v5
	s_nop 0
	v_cndmask_b32_e32 v1, v1, v4, vcc
	v_mul_lo_u32 v4, v2, v1
	v_add_u32_e32 v2, v4, v2
	v_cmp_ne_u32_e32 vcc, v3, v2
	s_and_saveexec_b64 s[18:19], vcc
	s_xor_b64 s[18:19], exec, s[18:19]
	s_cbranch_execz .LBB0_618
	buffer_inv sc1
	v_readlane_b32 s22, v255, 0
	v_readlane_b32 s23, v255, 1
	s_waitcnt lgkmcnt(0)
	s_nop 3
	global_load_dword v0, v17, s[22:23] sc1
	s_waitcnt vmcnt(0)
	v_cmp_eq_u32_e32 vcc, v0, v1
	s_and_saveexec_b64 s[22:23], vcc
	s_cbranch_execz .LBB0_617
	s_mov_b32 s24, 1
	s_mov_b64 s[26:27], 0
	s_branch .LBB0_608

.LBB0_674:
	s_or_b64 exec, exec, s[14:15]
	v_cvt_f32_u32_e32 v4, v2
	s_waitcnt vmcnt(0)
	v_readfirstlane_b32 s14, v3
	v_sub_u32_e32 v3, 0, v2
	v_rcp_iflag_f32_e32 v4, v4
	v_add_u32_e32 v5, s14, v1
	v_mul_f32_e32 v4, 0x4f7ffffe, v4
	v_cvt_u32_f32_e32 v4, v4
	v_mul_lo_u32 v1, v3, v4
	v_mul_hi_u32 v1, v4, v1
	v_add_u32_e32 v1, v4, v1
	v_mul_hi_u32 v1, v5, v1
	v_mul_lo_u32 v3, v1, v2
	v_sub_u32_e32 v3, v5, v3
	v_add_u32_e32 v4, 1, v1
	v_cmp_ge_u32_e32 vcc, v3, v2
	s_nop 1
	v_cndmask_b32_e32 v1, v1, v4, vcc
	v_sub_u32_e32 v4, v3, v2
	v_cndmask_b32_e32 v3, v3, v4, vcc
	v_add_u32_e32 v4, 1, v1
	v_cmp_ge_u32_e32 vcc, v3, v2
	v_add_u32_e32 v3, 1, v5
	s_nop 0
	v_cndmask_b32_e32 v1, v1, v4, vcc
	v_mul_lo_u32 v4, v2, v1
	v_add_u32_e32 v2, v4, v2
	v_cmp_ne_u32_e32 vcc, v3, v2
	s_and_saveexec_b64 s[14:15], vcc
	s_xor_b64 s[14:15], exec, s[14:15]
	s_cbranch_execz .LBB0_688
	buffer_inv sc1
	v_readlane_b32 s18, v255, 0
	v_readlane_b32 s19, v255, 1
	s_waitcnt lgkmcnt(0)
	s_nop 3
	global_load_dword v0, v17, s[18:19] sc1
	s_waitcnt vmcnt(0)
	v_cmp_eq_u32_e32 vcc, v0, v1
	s_and_saveexec_b64 s[18:19], vcc
	s_cbranch_execz .LBB0_687
	s_mov_b32 s36, 1
	s_mov_b64 s[22:23], 0
	s_branch .LBB0_678

.LBB0_687:
	s_or_b64 exec, exec, s[18:19]
	s_waitcnt vmcnt(0)
	s_waitcnt vmcnt(0)
.LBB0_688:
	s_andn2_saveexec_b64 s[14:15], s[14:15]
	s_cbranch_execz .LBB0_708
	s_mov_b64 s[14:15], exec
	buffer_wbl2 sc1
	buffer_inv sc1
	s_waitcnt lgkmcnt(0)
	s_waitcnt vmcnt(0)
	v_mbcnt_lo_u32_b32 v1, s14, 0
	v_mbcnt_hi_u32_b32 v1, s15, v1
	v_cmp_eq_u32_e32 vcc, 0, v1
	s_and_saveexec_b64 s[18:19], vcc
	s_cbranch_execz .LBB0_691
	s_bcnt1_i32_b64 s14, s[14:15]
	v_mov_b32_e32 v2, s14
	v_readlane_b32 s14, v255, 2
	v_readlane_b32 s15, v255, 3
	s_nop 4
	global_atomic_add v2, v17, v2, s[14:15] sc0

.LBB0_705:
	s_or_b64 exec, exec, s[14:15]
	s_mov_b64 s[14:15], exec
	v_mbcnt_lo_u32_b32 v0, s14, 0
	v_mbcnt_hi_u32_b32 v0, s15, v0
	v_cmp_eq_u32_e32 vcc, 0, v0
	s_waitcnt vmcnt(0)
	s_and_saveexec_b64 s[18:19], vcc
	s_cbranch_execz .LBB0_707
	s_bcnt1_i32_b64 s14, s[14:15]
	v_mov_b32_e32 v0, s14
	v_readlane_b32 s14, v255, 0
	v_readlane_b32 s15, v255, 1
	s_nop 4
	global_atomic_add v17, v0, s[14:15]

.LBB0_742:
	s_or_b64 exec, exec, s[14:15]
	v_cvt_f32_u32_e32 v4, v2
	s_waitcnt vmcnt(0)
	v_readfirstlane_b32 s14, v3
	v_sub_u32_e32 v3, 0, v2
	v_rcp_iflag_f32_e32 v4, v4
	v_add_u32_e32 v5, s14, v1
	v_mul_f32_e32 v4, 0x4f7ffffe, v4
	v_cvt_u32_f32_e32 v4, v4
	v_mul_lo_u32 v1, v3, v4
	v_mul_hi_u32 v1, v4, v1
	v_add_u32_e32 v1, v4, v1
	v_mul_hi_u32 v1, v5, v1
	v_mul_lo_u32 v3, v1, v2
	v_sub_u32_e32 v3, v5, v3
	v_add_u32_e32 v4, 1, v1
	v_cmp_ge_u32_e32 vcc, v3, v2
	s_nop 1
	v_cndmask_b32_e32 v1, v1, v4, vcc
	v_sub_u32_e32 v4, v3, v2
	v_cndmask_b32_e32 v3, v3, v4, vcc
	v_add_u32_e32 v4, 1, v1
	v_cmp_ge_u32_e32 vcc, v3, v2
	v_add_u32_e32 v3, 1, v5
	s_nop 0
	v_cndmask_b32_e32 v1, v1, v4, vcc
	v_mul_lo_u32 v4, v2, v1
	v_add_u32_e32 v2, v4, v2
	v_cmp_ne_u32_e32 vcc, v3, v2
	s_and_saveexec_b64 s[14:15], vcc
	s_xor_b64 s[14:15], exec, s[14:15]
	s_cbranch_execz .LBB0_756
	buffer_inv sc1
	v_readlane_b32 s18, v255, 0
	v_readlane_b32 s19, v255, 1
	s_waitcnt lgkmcnt(0)
	s_nop 3
	global_load_dword v0, v17, s[18:19] sc1
	s_waitcnt vmcnt(0)
	v_cmp_eq_u32_e32 vcc, v0, v1
	s_and_saveexec_b64 s[18:19], vcc
	s_cbranch_execz .LBB0_755
	s_mov_b32 s24, 1
	s_mov_b64 s[22:23], 0
	s_branch .LBB0_746

.LBB0_1034:
	s_mov_b64 s[14:15], exec
	buffer_wbl2 sc1
	buffer_inv sc1
	s_waitcnt lgkmcnt(0)
	s_waitcnt vmcnt(0)
	v_mbcnt_lo_u32_b32 v1, s14, 0
	v_mbcnt_hi_u32_b32 v1, s15, v1
	v_cmp_eq_u32_e32 vcc, 0, v1
	s_and_saveexec_b64 s[18:19], vcc
	s_cbranch_execz .LBB0_1036
	s_bcnt1_i32_b64 s14, s[14:15]
	v_mov_b32_e32 v2, s14
	v_readlane_b32 s14, v255, 2
	v_readlane_b32 s15, v255, 3
	s_nop 4
	global_atomic_add v2, v17, v2, s[14:15] sc0

.LBB0_1050:
	s_or_b64 exec, exec, s[14:15]
	s_mov_b64 s[14:15], exec
	v_mbcnt_lo_u32_b32 v0, s14, 0
	v_mbcnt_hi_u32_b32 v0, s15, v0
	v_cmp_eq_u32_e32 vcc, 0, v0
	s_waitcnt vmcnt(0)
	s_and_saveexec_b64 s[18:19], vcc
	s_cbranch_execnz .LBB0_1051
	s_getpc_b64 s[98:99]
